# third combination + the now-unread per-XCC relay atomic removed from the grid barrier's leader path
# baseline (speedup 1.0000x reference)
; __device__ __forceinline__ unsigned xb_ld(unsigned* p)              { return __hip_atomic_load(p, __ATOMIC_RELAXED, __HIP_MEMORY_SCOPE_AGENT); }
; __device__ __forceinline__ unsigned xb_add(unsigned* p, unsigned v) { return __hip_atomic_fetch_add(p, v, __ATOMIC_RELAXED, __HIP_MEMORY_SCOPE_AGENT); }
; #define XB_SPIN(cond, bar) do { unsigned _sp = 0; while (cond) { __builtin_amdgcn_s_sleep(1); \
;     if ((++_sp & 255u) == 0u) { if (xb_ld(&(bar)[XB_TMO])) break; if (_sp > XB_SPIN_CAP) { atomicAdd(&(bar)[XB_TMO], 1u); break; } } } } while (0)
; __device__ __forceinline__ void xcd_barrier(const XcdBarrier& b) {
;     ...
;             __builtin_amdgcn_fence(__ATOMIC_RELEASE, "agent");
;             asm volatile("s_waitcnt vmcnt(0)" ::: "memory");
;             const unsigned og = xb_add(&bar[XB_TOP], 1u);
;             const unsigned tg = og / nx;
;             if (og + 1u == (tg + 1u) * nx) xb_add(&bar[XB_TOPGEN], 1u);
;             else XB_SPIN(xb_ld(&bar[XB_TOPGEN]) == tg, bar);
;             __builtin_amdgcn_fence(__ATOMIC_ACQUIRE, "agent");
;             xb_add(&bar[XB_XGEN(b.x)], 1u);
;             asm volatile("s_waitcnt vmcnt(0)" ::: "memory");
.LBB0_119:
	s_or_b64 exec, exec, s[2:3]
	s_mov_b64 s[2:3], exec
	v_mbcnt_lo_u32_b32 v1, s2, 0
	v_mbcnt_hi_u32_b32 v1, s3, v1
	v_cmp_eq_u32_e32 vcc, 0, v1
	s_waitcnt vmcnt(0)
	buffer_inv sc1
	s_and_saveexec_b64 s[6:7], vcc
	s_cbranch_execz .LBB0_121
	s_bcnt1_i32_b64 s2, s[2:3]
	v_mov_b32_e32 v1, 0x2000
	v_mov_b32_e32 v2, s2
	s_nop 0
	s_nop 0

; __device__ __forceinline__ unsigned xb_ld(unsigned* p)              { return __hip_atomic_load(p, __ATOMIC_RELAXED, __HIP_MEMORY_SCOPE_AGENT); }
; __device__ __forceinline__ unsigned xb_add(unsigned* p, unsigned v) { return __hip_atomic_fetch_add(p, v, __ATOMIC_RELAXED, __HIP_MEMORY_SCOPE_AGENT); }
; #define XB_SPIN(cond, bar) do { unsigned _sp = 0; while (cond) { __builtin_amdgcn_s_sleep(1); \
;     if ((++_sp & 255u) == 0u) { if (xb_ld(&(bar)[XB_TMO])) break; if (_sp > XB_SPIN_CAP) { atomicAdd(&(bar)[XB_TMO], 1u); break; } } } } while (0)
; __device__ __forceinline__ void xcd_barrier(const XcdBarrier& b) {
;     ...
;             __builtin_amdgcn_fence(__ATOMIC_RELEASE, "agent");
;             asm volatile("s_waitcnt vmcnt(0)" ::: "memory");
;             const unsigned og = xb_add(&bar[XB_TOP], 1u);
;             const unsigned tg = og / nx;
;             if (og + 1u == (tg + 1u) * nx) xb_add(&bar[XB_TOPGEN], 1u);
;             else XB_SPIN(xb_ld(&bar[XB_TOPGEN]) == tg, bar);
;             __builtin_amdgcn_fence(__ATOMIC_ACQUIRE, "agent");
;             xb_add(&bar[XB_XGEN(b.x)], 1u);
;             asm volatile("s_waitcnt vmcnt(0)" ::: "memory");
.LBB0_2820:
	s_or_b64 exec, exec, s[4:5]
	s_mov_b64 s[4:5], exec
	v_mbcnt_lo_u32_b32 v0, s4, 0
	v_mbcnt_hi_u32_b32 v0, s5, v0
	v_cmp_eq_u32_e32 vcc, 0, v0
	s_waitcnt vmcnt(0)
	buffer_inv sc1
	s_and_saveexec_b64 s[6:7], vcc
	s_cbranch_execz .LBB0_2822
	s_bcnt1_i32_b64 s4, s[4:5]
	v_mov_b32_e32 v0, 0x2000
	v_mov_b32_e32 v1, s4
	s_nop 0
	s_nop 0
